# EPI-PIPE P11: GEMM4 whole-tile epilogue residual loads issued five row-groups ahead through a slot ring, vmcnt re-derived, stores never waited for (on SUBLN-LDS)
# baseline (speedup 1.0000x reference)
.LBB0_1388:
	s_lshl_b32 s4, s4, 8
	v_lshl_add_u32 v198, v149, 5, s4
	v_lshlrev_b32_e32 v199, 2, v197
	s_lshl_b32 s5, s40, 8
	v_lshlrev_b32_e32 v128, 6, v148
	v_add_u32_e32 v186, v198, v199
	v_add3_u32 v188, v150, s5, v128
	v_lshl_add_u64 v[128:129], s[44:45], 2, v[166:167]
	v_ashrrev_i32_e32 v187, 31, v186
	v_lshl_add_u64 v[128:129], v[186:187], 2, v[128:129]
	v_lshl_add_u64 v[190:191], v[128:129], 0, s[28:29]
	s_cmp_lt_i32 s63, 0
	s_mov_b64 s[4:5], -1
	s_cbranch_scc0 .LBB0_1390
	v_and_b32_e32 v128, 1, v197
	v_add_u32_e32 v129, 12, v199
	v_cmp_eq_u32_e32 vcc, 0, v128
	v_ashrrev_i32_e32 v189, 31, v188
	v_lshlrev_b64 v[130:131], 11, v[188:189]
	v_cndmask_b32_e32 v128, v129, v199, vcc
	v_add_u32_e32 v128, v128, v198
	v_ashrrev_i32_e32 v129, 31, v128
	v_lshl_add_u64 v[130:131], v[170:171], 0, v[130:131]
	v_lshlrev_b64 v[146:147], 1, v[128:129]
	v_lshl_add_u64 v[200:201], v[130:131], 0, v[146:147]
	global_load_dwordx4 v[140:143], v[190:191], off
	global_load_dwordx4 v[136:139], v[190:191], off offset:64
	global_load_dwordx4 v[132:135], v[190:191], off offset:512
	global_load_dwordx4 v[128:131], v[190:191], off offset:576
	s_mov_b64 s[76:77], 0x8000
	s_mov_b64 s[78:79], 0x28000
	v_mov_b32_e32 v250, v200
	v_mov_b32_e32 v251, v201
	global_load_dwordx4 v[230:233], v[250:251], off
	global_load_dwordx4 v[234:237], v[250:251], off offset:256
	v_lshl_add_u64 v[250:251], v[250:251], 0, s[76:77]
	global_load_dwordx4 v[238:241], v[250:251], off
	global_load_dwordx4 v[242:245], v[250:251], off offset:256
	v_lshl_add_u64 v[250:251], v[250:251], 0, s[76:77]
	global_load_dwordx4 v[246:249], v[250:251], off
	v_lshlrev_b64 v[156:157], 12, v[188:189]
	v_lshlrev_b64 v[144:145], 2, v[186:187]
	v_lshl_add_u64 v[156:157], s[0:1], 0, v[156:157]
	v_lshl_add_u64 v[202:203], v[156:157], 0, v[144:145]
	s_mov_b64 s[4:5], 0
	s_mov_b64 s[42:43], -1
	s_waitcnt vmcnt(4)
	s_nop 1
	v_mov_b32_e32 v152, v230
	v_mov_b32_e32 v153, v231
	v_mov_b32_e32 v154, v232
	v_mov_b32_e32 v155, v233
	global_load_dwordx4 v[230:233], v[250:251], off offset:256
	v_mov_b32_e32 v151, v154
	v_mov_b32_e32 v154, v155
	s_nop 0
	v_permlane16_swap_b32_e32 v152, v151
	v_permlane16_swap_b32_e32 v153, v154
	v_lshlrev_b32_e32 v156, 16, v152
	v_and_b32_e32 v157, 0xffff0000, v152
	v_lshlrev_b32_e32 v152, 16, v153
	v_and_b32_e32 v153, 0xffff0000, v153
	v_lshlrev_b32_e32 v204, 16, v151
	v_and_b32_e32 v205, 0xffff0000, v151
	v_lshlrev_b32_e32 v158, 16, v154
	v_and_b32_e32 v159, 0xffff0000, v154
	v_pk_fma_f32 v[154:155], v[62:63], v[142:143], v[152:153]
	v_pk_fma_f32 v[152:153], v[60:61], v[140:141], v[156:157]
	v_pk_fma_f32 v[158:159], v[58:59], v[138:139], v[158:159]
	v_pk_fma_f32 v[156:157], v[56:57], v[136:137], v[204:205]
	global_store_dwordx4 v[202:203], v[152:155], off
	global_store_dwordx4 v[202:203], v[156:159], off offset:64
	v_add_u32_e32 v200, 16, v188
	v_ashrrev_i32_e32 v201, 31, v200
	v_lshlrev_b64 v[156:157], 11, v[200:201]
	v_lshl_add_u64 v[156:157], v[170:171], 0, v[156:157]
	v_lshl_add_u64 v[204:205], v[156:157], 0, v[146:147]
	s_waitcnt vmcnt(6)
	s_nop 1
	v_mov_b32_e32 v152, v234
	v_mov_b32_e32 v153, v235
	v_mov_b32_e32 v154, v236
	v_mov_b32_e32 v155, v237
	v_lshl_add_u64 v[250:251], v[250:251], 0, s[76:77]
	global_load_dwordx4 v[234:237], v[250:251], off
	v_mov_b32_e32 v151, v154
	v_mov_b32_e32 v154, v155
	s_nop 0
	v_permlane16_swap_b32_e32 v152, v151
	v_permlane16_swap_b32_e32 v153, v154
	v_lshlrev_b32_e32 v156, 16, v152
	v_and_b32_e32 v157, 0xffff0000, v152
	v_lshlrev_b32_e32 v152, 16, v153
	v_and_b32_e32 v153, 0xffff0000, v153
	v_lshlrev_b32_e32 v206, 16, v151
	v_and_b32_e32 v207, 0xffff0000, v151
	v_lshlrev_b32_e32 v158, 16, v154
	v_and_b32_e32 v159, 0xffff0000, v154
	v_pk_fma_f32 v[154:155], v[30:31], v[134:135], v[152:153]
	v_pk_fma_f32 v[152:153], v[28:29], v[132:133], v[156:157]
	v_pk_fma_f32 v[158:159], v[26:27], v[130:131], v[158:159]
	v_pk_fma_f32 v[156:157], v[24:25], v[128:129], v[206:207]
	global_store_dwordx4 v[202:203], v[152:155], off offset:512
	global_store_dwordx4 v[202:203], v[156:159], off offset:576
	s_waitcnt vmcnt(8)
	s_nop 1
	v_mov_b32_e32 v152, v238
	v_mov_b32_e32 v153, v239
	v_mov_b32_e32 v154, v240
	v_mov_b32_e32 v155, v241
	global_load_dwordx4 v[238:241], v[250:251], off offset:256
	v_mov_b32_e32 v151, v154
	v_lshlrev_b64 v[156:157], 12, v[200:201]
	v_mov_b32_e32 v154, v155
	v_lshl_add_u64 v[156:157], s[0:1], 0, v[156:157]
	v_permlane16_swap_b32_e32 v152, v151
	v_permlane16_swap_b32_e32 v153, v154
	v_lshl_add_u64 v[200:201], v[156:157], 0, v[144:145]
	v_lshlrev_b32_e32 v156, 16, v152
	v_and_b32_e32 v157, 0xffff0000, v152
	v_lshlrev_b32_e32 v152, 16, v153
	v_and_b32_e32 v153, 0xffff0000, v153
	v_lshlrev_b32_e32 v202, 16, v151
	v_and_b32_e32 v203, 0xffff0000, v151
	v_lshlrev_b32_e32 v158, 16, v154
	v_and_b32_e32 v159, 0xffff0000, v154
	v_pk_fma_f32 v[154:155], v[54:55], v[142:143], v[152:153]
	v_pk_fma_f32 v[152:153], v[52:53], v[140:141], v[156:157]
	v_pk_fma_f32 v[158:159], v[50:51], v[138:139], v[158:159]
	v_pk_fma_f32 v[156:157], v[48:49], v[136:137], v[202:203]
	global_store_dwordx4 v[200:201], v[152:155], off
	global_store_dwordx4 v[200:201], v[156:159], off offset:64
	v_add_u32_e32 v202, 32, v188
	v_ashrrev_i32_e32 v203, 31, v202
	v_lshlrev_b64 v[156:157], 11, v[202:203]
	v_lshl_add_u64 v[156:157], v[170:171], 0, v[156:157]
	v_lshl_add_u64 v[204:205], v[156:157], 0, v[146:147]
	s_waitcnt vmcnt(10)
	s_nop 1
	v_mov_b32_e32 v152, v242
	v_mov_b32_e32 v153, v243
	v_mov_b32_e32 v154, v244
	v_mov_b32_e32 v155, v245
	v_lshl_add_u64 v[250:251], v[250:251], 0, s[78:79]
	global_load_dwordx4 v[242:245], v[250:251], off
	v_mov_b32_e32 v151, v154
	v_mov_b32_e32 v154, v155
	s_nop 0
	v_permlane16_swap_b32_e32 v152, v151
	v_permlane16_swap_b32_e32 v153, v154
	v_lshlrev_b32_e32 v156, 16, v152
	v_and_b32_e32 v157, 0xffff0000, v152
	v_lshlrev_b32_e32 v152, 16, v153
	v_and_b32_e32 v153, 0xffff0000, v153
	v_lshlrev_b32_e32 v206, 16, v151
	v_and_b32_e32 v207, 0xffff0000, v151
	v_lshlrev_b32_e32 v158, 16, v154
	v_and_b32_e32 v159, 0xffff0000, v154
	v_pk_fma_f32 v[154:155], v[22:23], v[134:135], v[152:153]
	v_pk_fma_f32 v[152:153], v[20:21], v[132:133], v[156:157]
	v_pk_fma_f32 v[158:159], v[18:19], v[130:131], v[158:159]
	v_pk_fma_f32 v[156:157], v[16:17], v[128:129], v[206:207]
	global_store_dwordx4 v[200:201], v[152:155], off offset:512
	global_store_dwordx4 v[200:201], v[156:159], off offset:576
	s_waitcnt vmcnt(12)
	s_nop 1
	v_mov_b32_e32 v152, v246
	v_mov_b32_e32 v153, v247
	v_mov_b32_e32 v154, v248
	v_mov_b32_e32 v155, v249
	global_load_dwordx4 v[246:249], v[250:251], off offset:256
	v_mov_b32_e32 v151, v154
	v_lshlrev_b64 v[156:157], 12, v[202:203]
	v_mov_b32_e32 v154, v155
	v_lshl_add_u64 v[156:157], s[0:1], 0, v[156:157]
	v_permlane16_swap_b32_e32 v152, v151
	v_permlane16_swap_b32_e32 v153, v154
	v_lshl_add_u64 v[200:201], v[156:157], 0, v[144:145]
	v_lshlrev_b32_e32 v156, 16, v152
	v_and_b32_e32 v157, 0xffff0000, v152
	v_lshlrev_b32_e32 v152, 16, v153
	v_and_b32_e32 v153, 0xffff0000, v153
	v_lshlrev_b32_e32 v202, 16, v151
	v_and_b32_e32 v203, 0xffff0000, v151
	v_lshlrev_b32_e32 v158, 16, v154
	v_and_b32_e32 v159, 0xffff0000, v154
	v_pk_fma_f32 v[154:155], v[46:47], v[142:143], v[152:153]
	v_pk_fma_f32 v[152:153], v[44:45], v[140:141], v[156:157]
	v_pk_fma_f32 v[158:159], v[42:43], v[138:139], v[158:159]
	v_pk_fma_f32 v[156:157], v[40:41], v[136:137], v[202:203]
	global_store_dwordx4 v[200:201], v[152:155], off
	global_store_dwordx4 v[200:201], v[156:159], off offset:64
	v_add_u32_e32 v202, 48, v188
	v_ashrrev_i32_e32 v203, 31, v202
	v_lshlrev_b64 v[156:157], 11, v[202:203]
	v_lshl_add_u64 v[156:157], v[170:171], 0, v[156:157]
	v_lshl_add_u64 v[204:205], v[156:157], 0, v[146:147]
	s_waitcnt vmcnt(14)
	s_nop 1
	v_mov_b32_e32 v152, v230
	v_mov_b32_e32 v153, v231
	v_mov_b32_e32 v154, v232
	v_mov_b32_e32 v155, v233
	v_lshl_add_u64 v[250:251], v[250:251], 0, s[76:77]
	global_load_dwordx4 v[230:233], v[250:251], off
	v_mov_b32_e32 v151, v154
	v_mov_b32_e32 v154, v155
	s_nop 0
	v_permlane16_swap_b32_e32 v152, v151
	v_permlane16_swap_b32_e32 v153, v154
	v_lshlrev_b32_e32 v156, 16, v152
	v_and_b32_e32 v157, 0xffff0000, v152
	v_lshlrev_b32_e32 v152, 16, v153
	v_and_b32_e32 v153, 0xffff0000, v153
	v_lshlrev_b32_e32 v206, 16, v151
	v_and_b32_e32 v207, 0xffff0000, v151
	v_lshlrev_b32_e32 v158, 16, v154
	v_and_b32_e32 v159, 0xffff0000, v154
	v_pk_fma_f32 v[154:155], v[14:15], v[134:135], v[152:153]
	v_pk_fma_f32 v[152:153], v[12:13], v[132:133], v[156:157]
	v_pk_fma_f32 v[158:159], v[10:11], v[130:131], v[158:159]
	v_pk_fma_f32 v[156:157], v[8:9], v[128:129], v[206:207]
	global_store_dwordx4 v[200:201], v[152:155], off offset:512
	global_store_dwordx4 v[200:201], v[156:159], off offset:576
	s_waitcnt vmcnt(14)
	s_nop 1
	v_mov_b32_e32 v152, v234
	v_mov_b32_e32 v153, v235
	v_mov_b32_e32 v154, v236
	v_mov_b32_e32 v155, v237
	global_load_dwordx4 v[234:237], v[250:251], off offset:256
	v_mov_b32_e32 v151, v154
	v_mov_b32_e32 v189, v155
	v_lshlrev_b64 v[156:157], 12, v[202:203]
	v_permlane16_swap_b32_e32 v152, v151
	v_permlane16_swap_b32_e32 v153, v189
	v_lshl_add_u64 v[156:157], s[0:1], 0, v[156:157]
	v_lshlrev_b32_e32 v154, 16, v152
	v_and_b32_e32 v155, 0xffff0000, v152
	v_lshlrev_b32_e32 v152, 16, v153
	v_and_b32_e32 v153, 0xffff0000, v153
	v_lshl_add_u64 v[156:157], v[156:157], 0, v[144:145]
	v_lshlrev_b32_e32 v158, 16, v151
	v_and_b32_e32 v159, 0xffff0000, v151
	v_lshlrev_b32_e32 v200, 16, v189
	v_and_b32_e32 v201, 0xffff0000, v189
	v_pk_fma_f32 v[142:143], v[38:39], v[142:143], v[152:153]
	v_pk_fma_f32 v[140:141], v[36:37], v[140:141], v[154:155]
	v_pk_fma_f32 v[138:139], v[34:35], v[138:139], v[200:201]
	v_pk_fma_f32 v[136:137], v[32:33], v[136:137], v[158:159]
	global_store_dwordx4 v[156:157], v[140:143], off
	global_store_dwordx4 v[156:157], v[136:139], off offset:64
	v_add_u32_e32 v158, 0x80, v188
	v_ashrrev_i32_e32 v159, 31, v158
	v_lshlrev_b64 v[140:141], 11, v[158:159]
	v_lshl_add_u64 v[140:141], v[170:171], 0, v[140:141]
	v_lshl_add_u64 v[200:201], v[140:141], 0, v[146:147]
	s_waitcnt vmcnt(14)
	s_nop 1
	v_mov_b32_e32 v136, v238
	v_mov_b32_e32 v137, v239
	v_mov_b32_e32 v138, v240
	v_mov_b32_e32 v139, v241
	v_lshl_add_u64 v[250:251], v[250:251], 0, s[76:77]
	global_load_dwordx4 v[238:241], v[250:251], off
	v_mov_b32_e32 v141, v138
	v_mov_b32_e32 v143, v139
	s_nop 0
	v_permlane16_swap_b32_e32 v136, v141
	v_permlane16_swap_b32_e32 v137, v143
	v_lshlrev_b32_e32 v138, 16, v136
	v_and_b32_e32 v139, 0xffff0000, v136
	v_lshlrev_b32_e32 v136, 16, v137
	v_and_b32_e32 v137, 0xffff0000, v137
	v_lshlrev_b32_e32 v140, 16, v141
	v_and_b32_e32 v141, 0xffff0000, v141
	v_lshlrev_b32_e32 v142, 16, v143
	v_and_b32_e32 v143, 0xffff0000, v143
	v_pk_fma_f32 v[134:135], v[6:7], v[134:135], v[136:137]
	v_pk_fma_f32 v[132:133], v[4:5], v[132:133], v[138:139]
	v_pk_fma_f32 v[130:131], v[2:3], v[130:131], v[142:143]
	v_pk_fma_f32 v[128:129], v[0:1], v[128:129], v[140:141]
	global_store_dwordx4 v[156:157], v[132:135], off offset:512
	global_store_dwordx4 v[156:157], v[128:131], off offset:576
	global_load_dwordx4 v[140:143], v[190:191], off
	global_load_dwordx4 v[136:139], v[190:191], off offset:64
	v_lshlrev_b64 v[128:129], 12, v[158:159]
	v_lshl_add_u64 v[128:129], s[0:1], 0, v[128:129]
	v_lshl_add_u64 v[202:203], v[128:129], 0, v[144:145]
	global_load_dwordx4 v[132:135], v[190:191], off offset:512
	global_load_dwordx4 v[128:131], v[190:191], off offset:576
	s_waitcnt vmcnt(18)
	s_nop 1
	v_mov_b32_e32 v152, v242
	v_mov_b32_e32 v153, v243
	v_mov_b32_e32 v154, v244
	v_mov_b32_e32 v155, v245
	global_load_dwordx4 v[242:245], v[250:251], off offset:256
	v_mov_b32_e32 v151, v154
	v_mov_b32_e32 v154, v155
	s_nop 0
	v_permlane16_swap_b32_e32 v152, v151
	v_permlane16_swap_b32_e32 v153, v154
	v_lshlrev_b32_e32 v156, 16, v152
	v_and_b32_e32 v157, 0xffff0000, v152
	v_lshlrev_b32_e32 v152, 16, v153
	v_and_b32_e32 v153, 0xffff0000, v153
	v_lshlrev_b32_e32 v204, 16, v151
	v_and_b32_e32 v205, 0xffff0000, v151
	v_lshlrev_b32_e32 v158, 16, v154
	v_and_b32_e32 v159, 0xffff0000, v154
	s_waitcnt vmcnt(4)
	v_pk_fma_f32 v[154:155], v[126:127], v[142:143], v[152:153]
	v_pk_fma_f32 v[152:153], v[124:125], v[140:141], v[156:157]
	s_waitcnt vmcnt(3)
	v_pk_fma_f32 v[158:159], v[122:123], v[138:139], v[158:159]
	v_pk_fma_f32 v[156:157], v[120:121], v[136:137], v[204:205]
	global_store_dwordx4 v[202:203], v[152:155], off
	global_store_dwordx4 v[202:203], v[156:159], off offset:64
	v_add_u32_e32 v200, 0x90, v188
	v_ashrrev_i32_e32 v201, 31, v200
	v_lshlrev_b64 v[156:157], 11, v[200:201]
	v_lshl_add_u64 v[156:157], v[170:171], 0, v[156:157]
	v_lshl_add_u64 v[204:205], v[156:157], 0, v[146:147]
	s_waitcnt vmcnt(3)
	s_nop 1
	v_mov_b32_e32 v152, v246
	v_mov_b32_e32 v153, v247
	v_mov_b32_e32 v154, v248
	v_mov_b32_e32 v155, v249
	v_lshl_add_u64 v[250:251], v[250:251], 0, s[76:77]
	global_load_dwordx4 v[246:249], v[250:251], off
	v_mov_b32_e32 v151, v154
	v_mov_b32_e32 v154, v155
	s_nop 0
	v_permlane16_swap_b32_e32 v152, v151
	v_permlane16_swap_b32_e32 v153, v154
	v_lshlrev_b32_e32 v156, 16, v152
	v_and_b32_e32 v157, 0xffff0000, v152
	v_lshlrev_b32_e32 v152, 16, v153
	v_and_b32_e32 v153, 0xffff0000, v153
	v_lshlrev_b32_e32 v206, 16, v151
	v_and_b32_e32 v207, 0xffff0000, v151
	v_lshlrev_b32_e32 v158, 16, v154
	v_and_b32_e32 v159, 0xffff0000, v154
	v_pk_fma_f32 v[154:155], v[94:95], v[134:135], v[152:153]
	v_pk_fma_f32 v[152:153], v[92:93], v[132:133], v[156:157]
	v_pk_fma_f32 v[158:159], v[90:91], v[130:131], v[158:159]
	v_pk_fma_f32 v[156:157], v[88:89], v[128:129], v[206:207]
	global_store_dwordx4 v[202:203], v[152:155], off offset:512
	global_store_dwordx4 v[202:203], v[156:159], off offset:576
	s_nop 1
	v_mov_b32_e32 v152, v230
	v_mov_b32_e32 v153, v231
	v_mov_b32_e32 v154, v232
	v_mov_b32_e32 v155, v233
	global_load_dwordx4 v[230:233], v[250:251], off offset:256
	v_mov_b32_e32 v151, v154
	v_lshlrev_b64 v[156:157], 12, v[200:201]
	v_mov_b32_e32 v154, v155
	v_lshl_add_u64 v[156:157], s[0:1], 0, v[156:157]
	v_permlane16_swap_b32_e32 v152, v151
	v_permlane16_swap_b32_e32 v153, v154
	v_lshl_add_u64 v[200:201], v[156:157], 0, v[144:145]
	v_lshlrev_b32_e32 v156, 16, v152
	v_and_b32_e32 v157, 0xffff0000, v152
	v_lshlrev_b32_e32 v152, 16, v153
	v_and_b32_e32 v153, 0xffff0000, v153
	v_lshlrev_b32_e32 v202, 16, v151
	v_and_b32_e32 v203, 0xffff0000, v151
	v_lshlrev_b32_e32 v158, 16, v154
	v_and_b32_e32 v159, 0xffff0000, v154
	v_pk_fma_f32 v[154:155], v[118:119], v[142:143], v[152:153]
	v_pk_fma_f32 v[152:153], v[116:117], v[140:141], v[156:157]
	v_pk_fma_f32 v[158:159], v[114:115], v[138:139], v[158:159]
	v_pk_fma_f32 v[156:157], v[112:113], v[136:137], v[202:203]
	global_store_dwordx4 v[200:201], v[152:155], off
	global_store_dwordx4 v[200:201], v[156:159], off offset:64
	v_add_u32_e32 v202, 0xa0, v188
	v_ashrrev_i32_e32 v203, 31, v202
	v_lshlrev_b64 v[156:157], 11, v[202:203]
	v_lshl_add_u64 v[156:157], v[170:171], 0, v[156:157]
	v_lshl_add_u64 v[204:205], v[156:157], 0, v[146:147]
	s_nop 1
	v_mov_b32_e32 v152, v234
	v_mov_b32_e32 v153, v235
	v_mov_b32_e32 v154, v236
	v_mov_b32_e32 v155, v237
	v_mov_b32_e32 v151, v154
	v_mov_b32_e32 v154, v155
	s_nop 0
	v_permlane16_swap_b32_e32 v152, v151
	v_permlane16_swap_b32_e32 v153, v154
	v_lshlrev_b32_e32 v156, 16, v152
	v_and_b32_e32 v157, 0xffff0000, v152
	v_lshlrev_b32_e32 v152, 16, v153
	v_and_b32_e32 v153, 0xffff0000, v153
	v_lshlrev_b32_e32 v206, 16, v151
	v_and_b32_e32 v207, 0xffff0000, v151
	v_lshlrev_b32_e32 v158, 16, v154
	v_and_b32_e32 v159, 0xffff0000, v154
	v_pk_fma_f32 v[154:155], v[86:87], v[134:135], v[152:153]
	v_pk_fma_f32 v[152:153], v[84:85], v[132:133], v[156:157]
	v_pk_fma_f32 v[158:159], v[82:83], v[130:131], v[158:159]
	v_pk_fma_f32 v[156:157], v[80:81], v[128:129], v[206:207]
	global_store_dwordx4 v[200:201], v[152:155], off offset:512
	global_store_dwordx4 v[200:201], v[156:159], off offset:576
	s_nop 1
	v_mov_b32_e32 v152, v238
	v_mov_b32_e32 v153, v239
	v_mov_b32_e32 v154, v240
	v_mov_b32_e32 v155, v241
	v_mov_b32_e32 v151, v154
	v_lshlrev_b64 v[156:157], 12, v[202:203]
	v_mov_b32_e32 v154, v155
	v_lshl_add_u64 v[156:157], s[0:1], 0, v[156:157]
	v_permlane16_swap_b32_e32 v152, v151
	v_permlane16_swap_b32_e32 v153, v154
	v_lshl_add_u64 v[200:201], v[156:157], 0, v[144:145]
	v_lshlrev_b32_e32 v156, 16, v152
	v_and_b32_e32 v157, 0xffff0000, v152
	v_lshlrev_b32_e32 v152, 16, v153
	v_and_b32_e32 v153, 0xffff0000, v153
	v_lshlrev_b32_e32 v202, 16, v151
	v_and_b32_e32 v203, 0xffff0000, v151
	v_lshlrev_b32_e32 v158, 16, v154
	v_and_b32_e32 v159, 0xffff0000, v154
	v_pk_fma_f32 v[154:155], v[110:111], v[142:143], v[152:153]
	v_pk_fma_f32 v[152:153], v[108:109], v[140:141], v[156:157]
	v_pk_fma_f32 v[158:159], v[106:107], v[138:139], v[158:159]
	v_pk_fma_f32 v[156:157], v[104:105], v[136:137], v[202:203]
	global_store_dwordx4 v[200:201], v[152:155], off
	global_store_dwordx4 v[200:201], v[156:159], off offset:64
	v_add_u32_e32 v202, 0xb0, v188
	v_ashrrev_i32_e32 v203, 31, v202
	v_lshlrev_b64 v[156:157], 11, v[202:203]
	v_lshl_add_u64 v[156:157], v[170:171], 0, v[156:157]
	v_lshl_add_u64 v[146:147], v[156:157], 0, v[146:147]
	s_waitcnt vmcnt(12)
	s_nop 1
	v_mov_b32_e32 v152, v242
	v_mov_b32_e32 v153, v243
	v_mov_b32_e32 v154, v244
	v_mov_b32_e32 v155, v245
	v_mov_b32_e32 v151, v154
	v_mov_b32_e32 v154, v155
	s_nop 0
	v_permlane16_swap_b32_e32 v152, v151
	v_permlane16_swap_b32_e32 v153, v154
	v_lshlrev_b32_e32 v156, 16, v152
	v_and_b32_e32 v157, 0xffff0000, v152
	v_lshlrev_b32_e32 v152, 16, v153
	v_and_b32_e32 v153, 0xffff0000, v153
	v_lshlrev_b32_e32 v204, 16, v151
	v_and_b32_e32 v205, 0xffff0000, v151
	v_lshlrev_b32_e32 v158, 16, v154
	v_and_b32_e32 v159, 0xffff0000, v154
	v_pk_fma_f32 v[154:155], v[78:79], v[134:135], v[152:153]
	v_pk_fma_f32 v[152:153], v[76:77], v[132:133], v[156:157]
	v_pk_fma_f32 v[158:159], v[74:75], v[130:131], v[158:159]
	v_pk_fma_f32 v[156:157], v[72:73], v[128:129], v[204:205]
	global_store_dwordx4 v[200:201], v[152:155], off offset:512
	global_store_dwordx4 v[200:201], v[156:159], off offset:576
	s_waitcnt vmcnt(11)
	s_nop 1
	v_mov_b32_e32 v152, v246
	v_mov_b32_e32 v153, v247
	v_mov_b32_e32 v154, v248
	v_mov_b32_e32 v155, v249
	v_mov_b32_e32 v151, v154
	v_mov_b32_e32 v159, v155
	v_lshlrev_b64 v[156:157], 12, v[202:203]
	v_permlane16_swap_b32_e32 v152, v151
	v_permlane16_swap_b32_e32 v153, v159
	v_lshl_add_u64 v[156:157], s[0:1], 0, v[156:157]
	v_lshlrev_b32_e32 v154, 16, v152
	v_and_b32_e32 v155, 0xffff0000, v152
	v_lshlrev_b32_e32 v152, 16, v153
	v_and_b32_e32 v153, 0xffff0000, v153
	v_lshl_add_u64 v[144:145], v[156:157], 0, v[144:145]
	v_lshlrev_b32_e32 v156, 16, v151
	v_and_b32_e32 v157, 0xffff0000, v151
	v_lshlrev_b32_e32 v158, 16, v159
	v_and_b32_e32 v159, 0xffff0000, v159
	v_pk_fma_f32 v[142:143], v[102:103], v[142:143], v[152:153]
	v_pk_fma_f32 v[140:141], v[100:101], v[140:141], v[154:155]
	v_pk_fma_f32 v[138:139], v[98:99], v[138:139], v[158:159]
	v_pk_fma_f32 v[136:137], v[96:97], v[136:137], v[156:157]
	global_store_dwordx4 v[144:145], v[140:143], off
	global_store_dwordx4 v[144:145], v[136:139], off offset:64
	s_waitcnt vmcnt(10)
	s_nop 1
	v_mov_b32_e32 v138, v230
	v_mov_b32_e32 v139, v231
	v_mov_b32_e32 v140, v232
	v_mov_b32_e32 v141, v233
	v_mov_b32_e32 v143, v140
	v_mov_b32_e32 v147, v141
	s_nop 0
	v_permlane16_swap_b32_e32 v138, v143
	v_permlane16_swap_b32_e32 v139, v147
	v_lshlrev_b32_e32 v140, 16, v138
	v_and_b32_e32 v141, 0xffff0000, v138
	v_lshlrev_b32_e32 v138, 16, v139
	v_and_b32_e32 v139, 0xffff0000, v139
	v_lshlrev_b32_e32 v142, 16, v143
	v_and_b32_e32 v143, 0xffff0000, v143
	v_lshlrev_b32_e32 v146, 16, v147
	v_and_b32_e32 v147, 0xffff0000, v147
	v_pk_fma_f32 v[134:135], v[70:71], v[134:135], v[138:139]
	v_pk_fma_f32 v[132:133], v[68:69], v[132:133], v[140:141]
	v_lshlrev_b64 v[136:137], 10, v[202:203]
	v_pk_fma_f32 v[130:131], v[66:67], v[130:131], v[146:147]
	v_pk_fma_f32 v[128:129], v[64:65], v[128:129], v[142:143]
	global_store_dwordx4 v[144:145], v[132:135], off offset:512
